# speedup vs baseline: 1.0417x; 1.0159x over previous
; #define NEG_INF (-__builtin_inff())
; DI void softmax_step(float (&sc)[16], AState& st, const KV& kv) {
;   float mx = NEG_INF;
; #pragma unroll
;   for (int i = 0; i < 16; ++i) mx = fmaxf(mx, sc[i]);
;   mx = fmaxf(mx, __shfl_xor(mx, 32));
;   const float mnew = fmaxf(st.m, mx);
;   const float meff = (mnew == NEG_INF) ? 0.f : mnew;
;   const float alpha = __expf(st.m - meff);
;   float rs = 0.f;
; #pragma unroll
;   for (int i = 0; i < 16; ++i) { sc[i] = __expf(sc[i] - meff); rs += sc[i]; }
;   st.l = st.l * alpha + rs;
;   st.m = mnew;
;   if (__any(alpha != 1.f)) {
; #pragma unroll
;     for (int i = 0; i < 16; ++i) { st.o0[i] *= alpha; st.o1[i] *= alpha; }
;   }
;   pv_tile(kv, sc, st);
; }
; DI void forget_group(const u16* R, const u16* T, const float* esuf, const float* ctot, const float* gh, u16* obuf, int hh, int g8, float kmax2, char* lds) {
;     ...
;         carry += tot;
;         softmax_step(sc, st, kv);
;         if (__all((zmax + carry - st.m) < -105.f)) done = true;
.LBB0_696:
	v_mov_b32_e32 v194, 0x3fb8aa3b
	v_mul_f32_e32 v195, 0xbfb8aa3b, v116
	v_fma_f32 v34, v34, v194, v195
	v_fma_f32 v35, v35, v194, v195
	v_exp_f32_e32 v34, v34
	v_fma_f32 v36, v36, v194, v195
	v_exp_f32_e32 v35, v35
	v_fma_f32 v37, v37, v194, v195
	v_exp_f32_e32 v36, v36
	v_fma_f32 v38, v38, v194, v195
	v_exp_f32_e32 v37, v37
	v_fma_f32 v39, v39, v194, v195
	v_fma_f32 v40, v40, v194, v195
	v_fma_f32 v41, v41, v194, v195
	v_add_f32_e32 v105, 0, v34
	v_exp_f32_e32 v38, v38
	v_add_f32_e32 v105, v35, v105
	v_exp_f32_e32 v39, v39
	v_exp_f32_e32 v40, v40
	v_exp_f32_e32 v41, v41
	v_add_f32_e32 v105, v36, v105
	v_fma_f32 v42, v42, v194, v195
	v_add_f32_e32 v105, v37, v105
	v_fma_f32 v43, v43, v194, v195
	v_add_f32_e32 v105, v38, v105
	v_exp_f32_e32 v42, v42
	v_fma_f32 v44, v44, v194, v195
	v_add_f32_e32 v105, v39, v105
	v_exp_f32_e32 v43, v43
	v_fma_f32 v45, v45, v194, v195
	v_cvt_pk_bf16_f32 v34, v34, v35
	v_cvt_pk_bf16_f32 v35, v36, v37
	v_cvt_pk_bf16_f32 v36, v38, v39
	v_cvt_pk_bf16_f32 v37, v40, v41
	v_add_f32_e32 v105, v40, v105
	v_exp_f32_e32 v44, v44
	v_fma_f32 v46, v46, v194, v195
	v_mfma_f32_32x32x16_bf16 v[18:33], v[90:93], v[34:37], v[18:33]
	v_add_f32_e32 v105, v41, v105
	v_exp_f32_e32 v45, v45
	v_fma_f32 v47, v47, v194, v195
	v_fma_f32 v48, v48, v194, v195
	v_fma_f32 v49, v49, v194, v195
	v_add_f32_e32 v105, v42, v105
	v_mfma_f32_32x32x16_bf16 v[2:17], v[82:85], v[34:37], v[2:17]
	v_exp_f32_e32 v46, v46
	v_add_f32_e32 v105, v43, v105
	v_exp_f32_e32 v47, v47
	v_exp_f32_e32 v48, v48
	v_exp_f32_e32 v49, v49
	v_add_f32_e32 v105, v44, v105
	v_add_f32_e32 v105, v45, v105
	v_add_f32_e32 v105, v46, v105
	v_add_f32_e32 v105, v47, v105
	v_cvt_pk_bf16_f32 v38, v42, v43
	v_cvt_pk_bf16_f32 v39, v44, v45
	v_cvt_pk_bf16_f32 v40, v46, v47
	v_cvt_pk_bf16_f32 v41, v48, v49
	v_add_f32_e32 v105, v48, v105
	v_add_f32_e32 v105, v49, v105
	v_mfma_f32_32x32x16_bf16 v[18:33], v[86:89], v[38:41], v[18:33]
	v_mul_f32_e32 v103, v103, v0
	s_waitcnt vmcnt(0)
	v_add_f32_e64 v102, v102, v104
	v_add_f32_e64 v103, v103, v105
	s_mov_b32 s2, 0xc2d20000
	v_add_f32_e32 v0, v109, v102
	v_sub_f32_e32 v0, v0, v115
	v_cmp_gt_f32_e32 vcc, s2, v0
	s_cmp_eq_u64 vcc, exec
	v_mfma_f32_32x32x16_bf16 v[2:17], v[78:81], v[38:41], v[2:17]
	s_cselect_b64 s[90:91], -1, 0
	v_mov_b32_e32 v105, v115
	s_branch .LBB0_698

; #define NEG_INF (-__builtin_inff())
; DI void softmax_step(float (&sc)[16], AState& st, const KV& kv) {
;   float mx = NEG_INF;
; #pragma unroll
;   for (int i = 0; i < 16; ++i) mx = fmaxf(mx, sc[i]);
;   mx = fmaxf(mx, __shfl_xor(mx, 32));
;   const float mnew = fmaxf(st.m, mx);
;   const float meff = (mnew == NEG_INF) ? 0.f : mnew;
;   const float alpha = __expf(st.m - meff);
;   float rs = 0.f;
; #pragma unroll
;   for (int i = 0; i < 16; ++i) { sc[i] = __expf(sc[i] - meff); rs += sc[i]; }
;   st.l = st.l * alpha + rs;
;   st.m = mnew;
;   if (__any(alpha != 1.f)) {
; #pragma unroll
;     for (int i = 0; i < 16; ++i) { st.o0[i] *= alpha; st.o1[i] *= alpha; }
;   }
;   pv_tile(kv, sc, st);
; }
; DI void forget_group(const u16* R, const u16* T, const float* esuf, const float* ctot, const float* gh, u16* obuf, int hh, int g8, float kmax2, char* lds) {
;     ...
;         carry += tot;
;         softmax_step(sc, st, kv);
;         if (__all((zmax + carry - st.m) < -105.f)) done = true;
.LBB0_704:
	v_mov_b32_e32 v194, 0x3fb8aa3b
	v_mul_f32_e32 v195, 0xbfb8aa3b, v115
	v_fma_f32 v34, v34, v194, v195
	v_fma_f32 v35, v35, v194, v195
	v_exp_f32_e32 v34, v34
	v_fma_f32 v36, v36, v194, v195
	v_exp_f32_e32 v35, v35
	v_fma_f32 v37, v37, v194, v195
	v_exp_f32_e32 v36, v36
	v_fma_f32 v38, v38, v194, v195
	v_exp_f32_e32 v37, v37
	v_fma_f32 v39, v39, v194, v195
	v_fma_f32 v40, v40, v194, v195
	v_fma_f32 v41, v41, v194, v195
	v_add_f32_e32 v105, 0, v34
	v_exp_f32_e32 v38, v38
	v_add_f32_e32 v105, v35, v105
	v_exp_f32_e32 v39, v39
	v_exp_f32_e32 v40, v40
	v_exp_f32_e32 v41, v41
	v_add_f32_e32 v105, v36, v105
	v_fma_f32 v42, v42, v194, v195
	v_add_f32_e32 v105, v37, v105
	v_fma_f32 v43, v43, v194, v195
	v_add_f32_e32 v105, v38, v105
	v_exp_f32_e32 v42, v42
	v_fma_f32 v44, v44, v194, v195
	v_add_f32_e32 v105, v39, v105
	v_exp_f32_e32 v43, v43
	v_fma_f32 v45, v45, v194, v195
	v_cvt_pk_bf16_f32 v34, v34, v35
	v_cvt_pk_bf16_f32 v35, v36, v37
	v_cvt_pk_bf16_f32 v36, v38, v39
	v_cvt_pk_bf16_f32 v37, v40, v41
	v_add_f32_e32 v105, v40, v105
	v_exp_f32_e32 v44, v44
	v_fma_f32 v46, v46, v194, v195
	v_mfma_f32_32x32x16_bf16 v[18:33], v[90:93], v[34:37], v[18:33]
	v_add_f32_e32 v105, v41, v105
	v_exp_f32_e32 v45, v45
	v_fma_f32 v47, v47, v194, v195
	v_fma_f32 v48, v48, v194, v195
	v_fma_f32 v49, v49, v194, v195
	v_add_f32_e32 v105, v42, v105
	v_mfma_f32_32x32x16_bf16 v[2:17], v[82:85], v[34:37], v[2:17]
	v_exp_f32_e32 v46, v46
	v_add_f32_e32 v105, v43, v105
	v_exp_f32_e32 v47, v47
	v_exp_f32_e32 v48, v48
	v_exp_f32_e32 v49, v49
	v_add_f32_e32 v105, v44, v105
	v_add_f32_e32 v105, v45, v105
	v_add_f32_e32 v105, v46, v105
	v_add_f32_e32 v105, v47, v105
	v_cvt_pk_bf16_f32 v38, v42, v43
	v_cvt_pk_bf16_f32 v39, v44, v45
	v_cvt_pk_bf16_f32 v40, v46, v47
	v_cvt_pk_bf16_f32 v41, v48, v49
	v_add_f32_e32 v105, v48, v105
	v_add_f32_e32 v105, v49, v105
	v_mfma_f32_32x32x16_bf16 v[18:33], v[86:89], v[38:41], v[18:33]
	v_mul_f32_e32 v103, v103, v0
	s_waitcnt vmcnt(0)
	v_add_f32_e64 v102, v102, v104
	v_add_f32_e64 v103, v103, v105
	s_mov_b32 s2, 0xc2d20000
	v_add_f32_e32 v0, v109, v102
	v_sub_f32_e32 v0, v0, v114
	v_cmp_gt_f32_e32 vcc, s2, v0
	s_cmp_eq_u64 vcc, exec
	v_mfma_f32_32x32x16_bf16 v[2:17], v[78:81], v[38:41], v[2:17]
	s_cselect_b64 s[86:87], -1, 0
	v_mov_b32_e32 v105, v114

; #define NEG_INF (-__builtin_inff())
; DI void softmax_step(float (&sc)[16], AState& st, const KV& kv) {
;   float mx = NEG_INF;
; #pragma unroll
;   for (int i = 0; i < 16; ++i) mx = fmaxf(mx, sc[i]);
;   mx = fmaxf(mx, __shfl_xor(mx, 32));
;   const float mnew = fmaxf(st.m, mx);
;   const float meff = (mnew == NEG_INF) ? 0.f : mnew;
;   const float alpha = __expf(st.m - meff);
;   float rs = 0.f;
; #pragma unroll
;   for (int i = 0; i < 16; ++i) { sc[i] = __expf(sc[i] - meff); rs += sc[i]; }
;   st.l = st.l * alpha + rs;
;   st.m = mnew;
;   if (__any(alpha != 1.f)) {
; #pragma unroll
;     for (int i = 0; i < 16; ++i) { st.o0[i] *= alpha; st.o1[i] *= alpha; }
;   }
;   pv_tile(kv, sc, st);
; }
.LBB0_728:
	v_mov_b32_e32 v194, 0x3fb8aa3b
	v_mul_f32_e32 v195, 0xbfb8aa3b, v61
	v_fma_f32 v15, v15, v194, v195
	v_fma_f32 v49, v49, v194, v195
	v_exp_f32_e32 v15, v15
	v_fma_f32 v48, v48, v194, v195
	v_exp_f32_e32 v49, v49
	v_exp_f32_e32 v63, v48
	v_add_f32_e32 v48, 0, v15
	v_add_f32_e32 v48, v49, v48
	v_add_f32_e32 v101, v63, v48
	v_fma_f32 v48, v51, v194, v195
	v_exp_f32_e32 v103, v48
	v_fma_f32 v48, v50, v194, v195
	v_exp_f32_e32 v104, v48
	v_fma_f32 v48, v52, v194, v195
	v_exp_f32_e32 v105, v48
	v_fma_f32 v48, v53, v194, v195
	v_exp_f32_e32 v106, v48
	v_fma_f32 v48, v55, v194, v195
	v_exp_f32_e32 v107, v48
	v_fma_f32 v48, v56, v194, v195
	v_exp_f32_e32 v56, v48
	v_fma_f32 v48, v57, v194, v195
	v_exp_f32_e32 v57, v48
	v_fma_f32 v48, v58, v194, v195
	v_exp_f32_e32 v58, v48
	v_fma_f32 v48, v59, v194, v195
	v_exp_f32_e32 v59, v48
	v_fma_f32 v48, v102, v194, v195
	v_exp_f32_e32 v102, v48
	v_fma_f32 v48, v60, v194, v195
	v_exp_f32_e32 v60, v48
	v_fma_f32 v48, v62, v194, v195
	v_exp_f32_e32 v62, v48
	v_cvt_pk_bf16_f32 v48, v15, v49
	v_cvt_pk_bf16_f32 v49, v63, v103
	v_cvt_pk_bf16_f32 v50, v104, v105
	v_cvt_pk_bf16_f32 v51, v106, v107
	v_fma_f32 v15, v54, v194, v195
	s_nop 0
	v_mfma_f32_32x32x16_bf16 v[16:31], v[84:87], v[48:51], v[16:31]
	v_exp_f32_e32 v15, v15
	v_cvt_pk_bf16_f32 v52, v56, v57
	v_cvt_pk_bf16_f32 v53, v58, v59
	v_cvt_pk_bf16_f32 v54, v102, v60
	v_cvt_pk_bf16_f32 v55, v62, v15
	v_mfma_f32_32x32x16_bf16 v[32:47], v[6:9], v[48:51], v[32:47]
	s_nop 0
	v_mfma_f32_32x32x16_bf16 v[16:31], v[10:13], v[52:55], v[16:31]
	v_add_f32_e32 v10, v103, v101
	v_add_f32_e32 v10, v104, v10
	v_add_f32_e32 v10, v105, v10
	v_add_f32_e32 v10, v106, v10
	v_add_f32_e32 v10, v107, v10
	v_add_f32_e32 v10, v56, v10
	v_add_f32_e32 v10, v57, v10
	v_add_f32_e32 v6, v58, v10
	v_mfma_f32_32x32x16_bf16 v[32:47], v[2:5], v[52:55], v[32:47]
	v_add_f32_e32 v6, v59, v6
	v_add_f32_e32 v6, v102, v6
	v_add_f32_e32 v6, v60, v6
	v_add_f32_e32 v6, v62, v6
	v_add_f32_e32 v6, v15, v6
	v_fmac_f32_e32 v6, v100, v0
	v_mov_b32_e32 v100, v6
	v_cndmask_b32_e64 v0, 0, 1, s[26:27]
	v_cmp_ne_u32_e64 s[46:47], 1, v0
	s_andn2_b64 vcc, exec, s[26:27]
	s_cbranch_vccz .LBB0_730
	s_branch .LBB0_731

; #define NEG_INF (-__builtin_inff())
; DI void softmax_step(float (&sc)[16], AState& st, const KV& kv) {
;   float mx = NEG_INF;
; #pragma unroll
;   for (int i = 0; i < 16; ++i) mx = fmaxf(mx, sc[i]);
;   mx = fmaxf(mx, __shfl_xor(mx, 32));
;   const float mnew = fmaxf(st.m, mx);
;   const float meff = (mnew == NEG_INF) ? 0.f : mnew;
;   const float alpha = __expf(st.m - meff);
;   float rs = 0.f;
; #pragma unroll
;   for (int i = 0; i < 16; ++i) { sc[i] = __expf(sc[i] - meff); rs += sc[i]; }
;   st.l = st.l * alpha + rs;
;   st.m = mnew;
;   if (__any(alpha != 1.f)) {
; #pragma unroll
;     for (int i = 0; i < 16; ++i) { st.o0[i] *= alpha; st.o1[i] *= alpha; }
;   }
;   pv_tile(kv, sc, st);
; }
; DI void band_run(AState& st, const bf16x8 (&q)[4], const Fam& f, int nstart, int ncount, int tq, int wtok, float nslope) {
;     ...
;   for (int k = 0; k < ncount; ++k) {
;     const int n0 = nstart + 32 * k;
;     if (k + 1 < ncount) load_kv<true, false>(nxt, f, n0 + 32, nullptr);
;     band_tile(cur, q, st, f, n0, tq, wtok, nslope);
;     cur = nxt;
;   }
.LBB0_790:
	v_mov_b32_e32 v194, 0x3fb8aa3b
	v_mul_f32_e32 v195, 0xbfb8aa3b, v114
	v_fma_f32 v34, v34, v194, v195
	v_fma_f32 v35, v35, v194, v195
	v_exp_f32_e32 v34, v34
	v_fma_f32 v36, v36, v194, v195
	v_exp_f32_e32 v35, v35
	v_fma_f32 v37, v37, v194, v195
	v_fma_f32 v38, v38, v194, v195
	v_fma_f32 v39, v39, v194, v195
	v_fma_f32 v40, v40, v194, v195
	v_fma_f32 v41, v41, v194, v195
	v_exp_f32_e32 v36, v36
	v_exp_f32_e32 v37, v37
	v_exp_f32_e32 v38, v38
	v_exp_f32_e32 v39, v39
	v_exp_f32_e32 v40, v40
	v_exp_f32_e32 v41, v41
	v_add_f32_e32 v115, 0, v34
	v_add_f32_e32 v115, v35, v115
	v_add_f32_e32 v115, v36, v115
	v_add_f32_e32 v115, v37, v115
	v_cvt_pk_bf16_f32 v34, v34, v35
	v_cvt_pk_bf16_f32 v35, v36, v37
	v_cvt_pk_bf16_f32 v36, v38, v39
	v_cvt_pk_bf16_f32 v37, v40, v41
	v_add_f32_e32 v115, v38, v115
	v_fma_f32 v42, v42, v194, v195
	v_mfma_f32_32x32x16_bf16 v[18:33], v[62:65], v[34:37], v[18:33]
	v_fma_f32 v43, v43, v194, v195
	v_fma_f32 v44, v44, v194, v195
	v_fma_f32 v45, v45, v194, v195
	v_fma_f32 v46, v46, v194, v195
	v_fma_f32 v47, v47, v194, v195
	v_fma_f32 v48, v48, v194, v195
	v_fma_f32 v38, v49, v194, v195
	v_mfma_f32_32x32x16_bf16 v[2:17], v[54:57], v[34:37], v[2:17]
	v_exp_f32_e32 v42, v42
	v_exp_f32_e32 v43, v43
	v_exp_f32_e32 v44, v44
	v_exp_f32_e32 v45, v45
	v_exp_f32_e32 v46, v46
	v_exp_f32_e32 v47, v47
	v_exp_f32_e32 v48, v48
	v_exp_f32_e32 v49, v38
	v_add_f32_e32 v115, v39, v115
	v_add_f32_e32 v115, v40, v115
	v_add_f32_e32 v115, v41, v115
	v_add_f32_e32 v115, v42, v115
	v_cvt_pk_bf16_f32 v38, v42, v43
	v_cvt_pk_bf16_f32 v39, v44, v45
	v_cvt_pk_bf16_f32 v40, v46, v47
	v_cvt_pk_bf16_f32 v41, v48, v49
	v_add_f32_e32 v42, v43, v115
	v_add_f32_e32 v42, v44, v42
	v_mfma_f32_32x32x16_bf16 v[18:33], v[58:61], v[38:41], v[18:33]
	v_add_f32_e32 v42, v45, v42
	v_add_f32_e32 v42, v46, v42
	v_add_f32_e32 v42, v47, v42
	v_add_f32_e32 v42, v48, v42
	s_addk_i32 s11, 0xfe00
	v_add_f32_e32 v132, v49, v42
	s_add_i32 s14, s48, s11
	v_mfma_f32_32x32x16_bf16 v[2:17], v[50:53], v[38:41], v[2:17]
	s_add_i32 s2, s2, 1
	s_add_i32 s49, s49, 32
	s_addk_i32 s53, 0x200
	v_fmac_f32_e32 v132, v134, v0
	s_cmp_lg_u32 s14, 0
	s_cbranch_scc1 .LBB0_786
	s_branch .LBB0_792

; #define NEG_INF (-__builtin_inff())
; DI void softmax_step(float (&sc)[16], AState& st, const KV& kv) {
;   float mx = NEG_INF;
; #pragma unroll
;   for (int i = 0; i < 16; ++i) mx = fmaxf(mx, sc[i]);
;   mx = fmaxf(mx, __shfl_xor(mx, 32));
;   const float mnew = fmaxf(st.m, mx);
;   const float meff = (mnew == NEG_INF) ? 0.f : mnew;
;   const float alpha = __expf(st.m - meff);
;   float rs = 0.f;
; #pragma unroll
;   for (int i = 0; i < 16; ++i) { sc[i] = __expf(sc[i] - meff); rs += sc[i]; }
;   st.l = st.l * alpha + rs;
;   st.m = mnew;
;   if (__any(alpha != 1.f)) {
; #pragma unroll
;     for (int i = 0; i < 16; ++i) { st.o0[i] *= alpha; st.o1[i] *= alpha; }
;   }
;   pv_tile(kv, sc, st);
; }
; DI void band_run(AState& st, const bf16x8 (&q)[4], const Fam& f, int nstart, int ncount, int tq, int wtok, float nslope) {
;     ...
;   for (int k = 0; k < ncount; ++k) {
;     const int n0 = nstart + 32 * k;
;     if (k + 1 < ncount) load_kv<true, false>(nxt, f, n0 + 32, nullptr);
;     band_tile(cur, q, st, f, n0, tq, wtok, nslope);
;     cur = nxt;
;   }
.LBB0_798:
	v_mov_b32_e32 v194, 0x3fb8aa3b
	v_mul_f32_e32 v195, 0xbfb8aa3b, v114
	v_fma_f32 v34, v34, v194, v195
	v_fma_f32 v35, v35, v194, v195
	v_exp_f32_e32 v34, v34
	v_fma_f32 v36, v36, v194, v195
	v_exp_f32_e32 v35, v35
	v_fma_f32 v37, v37, v194, v195
	v_fma_f32 v38, v38, v194, v195
	v_fma_f32 v39, v39, v194, v195
	v_fma_f32 v40, v40, v194, v195
	v_fma_f32 v41, v41, v194, v195
	v_exp_f32_e32 v36, v36
	v_exp_f32_e32 v37, v37
	v_exp_f32_e32 v38, v38
	v_exp_f32_e32 v39, v39
	v_exp_f32_e32 v40, v40
	v_exp_f32_e32 v41, v41
	v_add_f32_e32 v115, 0, v34
	v_add_f32_e32 v115, v35, v115
	v_add_f32_e32 v115, v36, v115
	v_add_f32_e32 v115, v37, v115
	v_cvt_pk_bf16_f32 v34, v34, v35
	v_cvt_pk_bf16_f32 v35, v36, v37
	v_cvt_pk_bf16_f32 v36, v38, v39
	v_cvt_pk_bf16_f32 v37, v40, v41
	v_add_f32_e32 v115, v38, v115
	v_fma_f32 v42, v42, v194, v195
	v_mfma_f32_32x32x16_bf16 v[18:33], v[62:65], v[34:37], v[18:33]
	v_fma_f32 v43, v43, v194, v195
	v_fma_f32 v44, v44, v194, v195
	v_fma_f32 v45, v45, v194, v195
	v_fma_f32 v46, v46, v194, v195
	v_fma_f32 v47, v47, v194, v195
	v_fma_f32 v48, v48, v194, v195
	v_fma_f32 v38, v49, v194, v195
	v_mfma_f32_32x32x16_bf16 v[2:17], v[54:57], v[34:37], v[2:17]
	v_exp_f32_e32 v42, v42
	v_exp_f32_e32 v43, v43
	v_exp_f32_e32 v44, v44
	v_exp_f32_e32 v45, v45
	v_exp_f32_e32 v46, v46
	v_exp_f32_e32 v47, v47
	v_exp_f32_e32 v48, v48
	v_exp_f32_e32 v49, v38
	v_add_f32_e32 v115, v39, v115
	v_add_f32_e32 v115, v40, v115
	v_add_f32_e32 v115, v41, v115
	v_add_f32_e32 v115, v42, v115
	v_cvt_pk_bf16_f32 v38, v42, v43
	v_cvt_pk_bf16_f32 v39, v44, v45
	v_cvt_pk_bf16_f32 v40, v46, v47
	v_cvt_pk_bf16_f32 v41, v48, v49
	v_add_f32_e32 v42, v43, v115
	v_add_f32_e32 v42, v44, v42
	v_mfma_f32_32x32x16_bf16 v[18:33], v[58:61], v[38:41], v[18:33]
	v_add_f32_e32 v42, v45, v42
	v_add_f32_e32 v42, v46, v42
	v_add_f32_e32 v42, v47, v42
	v_add_f32_e32 v42, v48, v42
	s_addk_i32 s23, 0xff80
	v_add_f32_e32 v190, v49, v42
	s_add_i32 s14, s53, s23
	v_mfma_f32_32x32x16_bf16 v[2:17], v[50:53], v[38:41], v[2:17]
	s_add_i32 s2, s2, 1
	s_addk_i32 s54, 0x80
	s_add_i32 s10, s10, 32
	v_fmac_f32_e32 v190, v132, v0
	s_cmp_lg_u32 s14, 0
	s_cbranch_scc1 .LBB0_794
	s_branch .LBB0_800

; #define NEG_INF (-__builtin_inff())
; DI void softmax_step(float (&sc)[16], AState& st, const KV& kv) {
;   float mx = NEG_INF;
; #pragma unroll
;   for (int i = 0; i < 16; ++i) mx = fmaxf(mx, sc[i]);
;   mx = fmaxf(mx, __shfl_xor(mx, 32));
;   const float mnew = fmaxf(st.m, mx);
;   const float meff = (mnew == NEG_INF) ? 0.f : mnew;
;   const float alpha = __expf(st.m - meff);
;   float rs = 0.f;
; #pragma unroll
;   for (int i = 0; i < 16; ++i) { sc[i] = __expf(sc[i] - meff); rs += sc[i]; }
;   st.l = st.l * alpha + rs;
;   st.m = mnew;
;   if (__any(alpha != 1.f)) {
; #pragma unroll
;     for (int i = 0; i < 16; ++i) { st.o0[i] *= alpha; st.o1[i] *= alpha; }
;   }
;   pv_tile(kv, sc, st);
; }
; DI void band_run(AState& st, const bf16x8 (&q)[4], const Fam& f, int nstart, int ncount, int tq, int wtok, float nslope) {
;     ...
;   for (int k = 0; k < ncount; ++k) {
;     const int n0 = nstart + 32 * k;
;     if (k + 1 < ncount) load_kv<true, false>(nxt, f, n0 + 32, nullptr);
;     band_tile(cur, q, st, f, n0, tq, wtok, nslope);
;     cur = nxt;
;   }
.LBB0_806:
	v_mov_b32_e32 v194, 0x3fb8aa3b
	v_mul_f32_e32 v195, 0xbfb8aa3b, v150
	v_fma_f32 v66, v66, v194, v195
	v_fma_f32 v67, v67, v194, v195
	v_exp_f32_e32 v66, v66
	v_fma_f32 v68, v68, v194, v195
	v_exp_f32_e32 v67, v67
	v_fma_f32 v69, v69, v194, v195
	v_fma_f32 v70, v70, v194, v195
	v_fma_f32 v71, v71, v194, v195
	v_fma_f32 v72, v72, v194, v195
	v_fma_f32 v73, v73, v194, v195
	v_exp_f32_e32 v68, v68
	v_exp_f32_e32 v69, v69
	v_exp_f32_e32 v70, v70
	v_exp_f32_e32 v71, v71
	v_exp_f32_e32 v72, v72
	v_exp_f32_e32 v73, v73
	v_add_f32_e32 v151, 0, v66
	v_add_f32_e32 v151, v67, v151
	v_add_f32_e32 v151, v68, v151
	v_add_f32_e32 v151, v69, v151
	v_cvt_pk_bf16_f32 v66, v66, v67
	v_cvt_pk_bf16_f32 v67, v68, v69
	v_cvt_pk_bf16_f32 v68, v70, v71
	v_cvt_pk_bf16_f32 v69, v72, v73
	v_add_f32_e32 v151, v70, v151
	v_fma_f32 v74, v74, v194, v195
	v_mfma_f32_32x32x16_bf16 v[50:65], v[110:113], v[66:69], v[50:65]
	v_fma_f32 v75, v75, v194, v195
	v_fma_f32 v76, v76, v194, v195
	v_fma_f32 v77, v77, v194, v195
	v_fma_f32 v78, v78, v194, v195
	v_fma_f32 v147, v147, v194, v195
	v_fma_f32 v148, v148, v194, v195
	v_fma_f32 v70, v149, v194, v195
	v_mfma_f32_32x32x16_bf16 v[34:49], v[102:105], v[66:69], v[34:49]
	v_exp_f32_e32 v74, v74
	v_exp_f32_e32 v75, v75
	v_exp_f32_e32 v76, v76
	v_exp_f32_e32 v77, v77
	v_exp_f32_e32 v78, v78
	v_exp_f32_e32 v147, v147
	v_exp_f32_e32 v148, v148
	v_exp_f32_e32 v110, v70
	v_add_f32_e32 v151, v71, v151
	v_add_f32_e32 v151, v72, v151
	v_add_f32_e32 v151, v73, v151
	v_cvt_pk_bf16_f32 v70, v74, v75
	v_cvt_pk_bf16_f32 v71, v76, v77
	v_cvt_pk_bf16_f32 v72, v78, v147
	v_cvt_pk_bf16_f32 v73, v148, v110
	v_add_f32_e32 v74, v74, v151
	v_add_f32_e32 v74, v75, v74
	v_mfma_f32_32x32x16_bf16 v[50:65], v[106:109], v[70:73], v[50:65]
	v_add_f32_e32 v74, v76, v74
	v_add_f32_e32 v74, v77, v74
	v_add_f32_e32 v74, v78, v74
	v_add_f32_e32 v74, v147, v74
	v_add_f32_e32 v74, v148, v74
	s_sub_i32 s12, s12, 32
	v_add_f32_e32 v66, v110, v74
	v_mfma_f32_32x32x16_bf16 v[34:49], v[98:101], v[70:73], v[34:49]
	s_add_i32 s14, s13, s12
	s_add_i32 s11, s11, 1
	s_add_i32 s10, s10, 32
	v_fmac_f32_e32 v66, v193, v0
	s_cmp_lg_u32 s14, 0
	s_cbranch_scc1 .LBB0_802
	v_mov_b32_e32 v164, v170
	v_mov_b32_e32 v165, v171
	s_branch .LBB0_737

; #define NEG_INF (-__builtin_inff())
; DI void softmax_step(float (&sc)[16], AState& st, const KV& kv) {
;   float mx = NEG_INF;
; #pragma unroll
;   for (int i = 0; i < 16; ++i) mx = fmaxf(mx, sc[i]);
;   mx = fmaxf(mx, __shfl_xor(mx, 32));
;   const float mnew = fmaxf(st.m, mx);
;   const float meff = (mnew == NEG_INF) ? 0.f : mnew;
;   const float alpha = __expf(st.m - meff);
;   float rs = 0.f;
; #pragma unroll
;   for (int i = 0; i < 16; ++i) { sc[i] = __expf(sc[i] - meff); rs += sc[i]; }
;   st.l = st.l * alpha + rs;
;   st.m = mnew;
;   if (__any(alpha != 1.f)) {
; #pragma unroll
;     for (int i = 0; i < 16; ++i) { st.o0[i] *= alpha; st.o1[i] *= alpha; }
;   }
;   pv_tile(kv, sc, st);
; }
; DI void nsa_group(const u16* R, const u16* T, const float* Oc, const float* Ow, const u32* selm, const float* bg, const float* gh, u16* obuf, int qtile, char* lds) {
;     ...
;         softmax_step(sc, st, kv);
;       }
;       if (ld2) {
;         *reinterpret_cast<u32x4*>(lds + (buf ^ 1) * (2 * NG_TB) + kdst) = rk;
;         *reinterpret_cast<u32x4*>(lds + (buf ^ 1) * (2 * NG_TB) + vdst) = rv;
;       }
;       __syncthreads();
;       if (!hA2) break;
;       nA = nA2; nB = nB2; lbA = lbA2; lbB = lbB2; hB = hB2; buf ^= 1;
.LBB0_1192:
	v_mov_b32_e32 v194, 0x3fb8aa3b
	v_mul_f32_e32 v195, 0xbfb8aa3b, v61
	v_fma_f32 v52, v52, v194, v195
	v_fma_f32 v63, v130, v194, v195
	v_fma_f32 v130, v131, v194, v195
	v_exp_f32_e32 v131, v52
	v_fma_f32 v52, v53, v194, v195
	v_exp_f32_e32 v134, v52
	v_fma_f32 v52, v54, v194, v195
	v_exp_f32_e32 v135, v52
	v_fma_f32 v52, v55, v194, v195
	v_exp_f32_e32 v136, v52
	v_fma_f32 v52, v56, v194, v195
	v_exp_f32_e32 v56, v52
	v_fma_f32 v52, v57, v194, v195
	v_exp_f32_e32 v57, v52
	v_fma_f32 v52, v132, v194, v195
	v_exp_f32_e32 v132, v52
	v_fma_f32 v52, v59, v194, v195
	v_fma_f32 v15, v15, v194, v195
	v_fma_f32 v14, v14, v194, v195
	v_exp_f32_e32 v59, v52
	v_fma_f32 v52, v60, v194, v195
	v_exp_f32_e32 v63, v63
	v_exp_f32_e32 v15, v15
	v_exp_f32_e32 v14, v14
	v_exp_f32_e32 v130, v130
	v_exp_f32_e32 v60, v52
	v_fma_f32 v52, v133, v194, v195
	v_exp_f32_e32 v133, v52
	v_fma_f32 v52, v62, v194, v195
	v_add_f32_e32 v128, 0, v63
	v_exp_f32_e32 v62, v52
	v_cvt_pk_bf16_f32 v52, v63, v15
	v_cvt_pk_bf16_f32 v53, v14, v130
	v_cvt_pk_bf16_f32 v54, v131, v134
	v_cvt_pk_bf16_f32 v55, v135, v136
	v_add_f32_e32 v128, v15, v128
	v_add_f32_e32 v128, v14, v128
	s_waitcnt lgkmcnt(3)
	v_mfma_f32_32x32x16_bf16 v[32:47], v[48:51], v[52:55], v[32:47]
	v_fma_f32 v14, v58, v194, v195
	v_exp_f32_e32 v14, v14
	v_cvt_pk_bf16_f32 v48, v56, v57
	v_cvt_pk_bf16_f32 v49, v132, v59
	v_cvt_pk_bf16_f32 v50, v60, v133
	v_cvt_pk_bf16_f32 v51, v62, v14
	s_waitcnt lgkmcnt(1)
	v_mfma_f32_32x32x16_bf16 v[16:31], v[6:9], v[52:55], v[16:31]
	v_mfma_f32_32x32x16_bf16 v[32:47], v[10:13], v[48:51], v[32:47]
	v_add_f32_e32 v10, v130, v128
	v_add_f32_e32 v10, v131, v10
	v_add_f32_e32 v10, v134, v10
	v_add_f32_e32 v10, v135, v10
	v_add_f32_e32 v10, v136, v10
	v_add_f32_e32 v10, v56, v10
	v_add_f32_e32 v10, v57, v10
	v_add_f32_e32 v6, v132, v10
	s_waitcnt lgkmcnt(0)
	v_mfma_f32_32x32x16_bf16 v[16:31], v[2:5], v[48:51], v[16:31]
	v_add_f32_e32 v6, v59, v6
	v_add_f32_e32 v6, v60, v6
	v_add_f32_e32 v6, v133, v6
	v_add_f32_e32 v6, v62, v6
	v_add_f32_e32 v6, v14, v6
	v_fmac_f32_e32 v6, v94, v0
	v_mov_b32_e32 v94, v6
	s_xor_b32 s11, s11, 1
	s_and_saveexec_b64 s[48:49], s[70:71]
	s_cbranch_execnz .LBB0_1194
	s_branch .LBB0_1195

; __global__ void __launch_bounds__(512, 2) mega(Params P) {
;     ...
;         gemm256_unit<3>(UO, WUP, 1024, pm * 256, pn * 256, dyn_lds, [&](const acc4 (&acc)[2][2][4][2], int wr, int wc, int fr, int fq) {
; #pragma unroll
;           for (int ai = 0; ai < 2; ++ai)
; #pragma unroll
;             for (int m = 0; m < 4; ++m) {
;               const int row = pm * 256 + ai * 128 + wr * 64 + m * 16 + fr;
; #pragma unroll
;               for (int bj = 0; bj < 2; ++bj)
; #pragma unroll
;                 for (int n = 0; n < 2; ++n) {
;                   const int col = pn * 256 + bj * 128 + wc * 32 + n * 16 + fq * 4;
;                   const acc4 v = acc[ai][bj][m][n];
;                   const float v0 = fmaxf(v[0], 0.f), v1 = fmaxf(v[1], 0.f), v2 = fmaxf(v[2], 0.f), v3 = fmaxf(v[3], 0.f);
;                   u32x2 pk = {pack2(v0 * v0, v1 * v1), pack2(v2 * v2, v3 * v3)};
;                   *reinterpret_cast<u32x2*>(ABUF + (size_t)row * DFF + col) = pk;
;                 }
;             }
;         });
.LBB0_1369:
	v_readlane_b32 s10, v255, 56
	s_lshl_b32 s10, s10, 8
	v_readlane_b32 s12, v255, 55
	v_lshl_or_b32 v0, v0, 2, s10
	v_lshl_or_b32 v134, s11, 5, v0
	v_lshl_add_u32 v130, s12, 8, v130
	v_lshlrev_b32_e32 v131, 13, v130
	v_lshl_add_u32 v131, v134, 1, v131
	v_and_b32_e32 v132, 16, v159
	v_lshrrev_b32_e32 v133, 1, v132
	v_add_u32_e32 v132, v132, v133
	v_add_u32_e32 v131, v131, v132
	s_mov_b64 s[100:101], s[82:83]
	v_max_f32_e32 v126, 0, v126
	v_max_f32_e32 v127, 0, v127
	v_max_f32_e32 v128, 0, v128
	v_max_f32_e32 v129, 0, v129
	v_max_f32_e32 v118, 0, v118
	v_max_f32_e32 v119, 0, v119
	v_max_f32_e32 v120, 0, v120
	v_max_f32_e32 v121, 0, v121
	v_mul_f32_e32 v126, v126, v126
	v_mul_f32_e32 v127, v127, v127
	v_mul_f32_e32 v128, v128, v128
	v_mul_f32_e32 v129, v129, v129
	v_mul_f32_e32 v118, v118, v118
	v_mul_f32_e32 v119, v119, v119
	v_mul_f32_e32 v120, v120, v120
	v_mul_f32_e32 v121, v121, v121
	v_cvt_pk_bf16_f32 v126, v126, v127
	v_cvt_pk_bf16_f32 v127, v128, v129
	v_cvt_pk_bf16_f32 v128, v118, v119
	v_cvt_pk_bf16_f32 v129, v120, v121
	s_nop 1
	v_permlane16_swap_b32_e32 v126, v128
	v_permlane16_swap_b32_e32 v127, v129
	global_store_dwordx4 v131, v[126:129], s[100:101]
	v_max_f32_e32 v122, 0, v122
	v_max_f32_e32 v123, 0, v123
	v_max_f32_e32 v124, 0, v124
	v_max_f32_e32 v125, 0, v125
	v_max_f32_e32 v114, 0, v114
	v_max_f32_e32 v115, 0, v115
	v_max_f32_e32 v116, 0, v116
	v_max_f32_e32 v117, 0, v117
	v_mul_f32_e32 v122, v122, v122
	v_mul_f32_e32 v123, v123, v123
	v_mul_f32_e32 v124, v124, v124
	v_mul_f32_e32 v125, v125, v125
	v_mul_f32_e32 v114, v114, v114
	v_mul_f32_e32 v115, v115, v115
	v_mul_f32_e32 v116, v116, v116
	v_mul_f32_e32 v117, v117, v117
	v_cvt_pk_bf16_f32 v122, v122, v123
	v_cvt_pk_bf16_f32 v123, v124, v125
	v_cvt_pk_bf16_f32 v124, v114, v115
	v_cvt_pk_bf16_f32 v125, v116, v117
	s_nop 1
	v_permlane16_swap_b32_e32 v122, v124
	v_permlane16_swap_b32_e32 v123, v125
	global_store_dwordx4 v131, v[122:125], s[100:101] offset:256
	s_add_u32 s100, s100, 0x20000
	s_addc_u32 s101, s101, 0
	v_max_f32_e32 v110, 0, v110
	v_max_f32_e32 v111, 0, v111
	v_max_f32_e32 v112, 0, v112
	v_max_f32_e32 v113, 0, v113
	v_max_f32_e32 v102, 0, v102
	v_max_f32_e32 v103, 0, v103
	v_max_f32_e32 v104, 0, v104
	v_max_f32_e32 v105, 0, v105
	v_mul_f32_e32 v110, v110, v110
	v_mul_f32_e32 v111, v111, v111
	v_mul_f32_e32 v112, v112, v112
	v_mul_f32_e32 v113, v113, v113
	v_mul_f32_e32 v102, v102, v102
	v_mul_f32_e32 v103, v103, v103
	v_mul_f32_e32 v104, v104, v104
	v_mul_f32_e32 v105, v105, v105
	v_cvt_pk_bf16_f32 v110, v110, v111
	v_cvt_pk_bf16_f32 v111, v112, v113
	v_cvt_pk_bf16_f32 v112, v102, v103
	v_cvt_pk_bf16_f32 v113, v104, v105
	s_nop 1
	v_permlane16_swap_b32_e32 v110, v112
	v_permlane16_swap_b32_e32 v111, v113
	global_store_dwordx4 v131, v[110:113], s[100:101]
	v_max_f32_e32 v106, 0, v106
	v_max_f32_e32 v107, 0, v107
	v_max_f32_e32 v108, 0, v108
	v_max_f32_e32 v109, 0, v109
	v_max_f32_e32 v98, 0, v98
	v_max_f32_e32 v99, 0, v99
	v_max_f32_e32 v100, 0, v100
	v_max_f32_e32 v101, 0, v101
	v_mul_f32_e32 v106, v106, v106
	v_mul_f32_e32 v107, v107, v107
	v_mul_f32_e32 v108, v108, v108
	v_mul_f32_e32 v109, v109, v109
	v_mul_f32_e32 v98, v98, v98
	v_mul_f32_e32 v99, v99, v99
	v_mul_f32_e32 v100, v100, v100
	v_mul_f32_e32 v101, v101, v101
	v_cvt_pk_bf16_f32 v106, v106, v107
	v_cvt_pk_bf16_f32 v107, v108, v109
	v_cvt_pk_bf16_f32 v108, v98, v99
	v_cvt_pk_bf16_f32 v109, v100, v101
	s_nop 1
	v_permlane16_swap_b32_e32 v106, v108
	v_permlane16_swap_b32_e32 v107, v109
	global_store_dwordx4 v131, v[106:109], s[100:101] offset:256
	s_add_u32 s100, s100, 0x20000
	s_addc_u32 s101, s101, 0
	v_max_f32_e32 v94, 0, v94
	v_max_f32_e32 v95, 0, v95
	v_max_f32_e32 v96, 0, v96
	v_max_f32_e32 v97, 0, v97
	v_max_f32_e32 v86, 0, v86
	v_max_f32_e32 v87, 0, v87
	v_max_f32_e32 v88, 0, v88
	v_max_f32_e32 v89, 0, v89
	v_mul_f32_e32 v94, v94, v94
	v_mul_f32_e32 v95, v95, v95
	v_mul_f32_e32 v96, v96, v96
	v_mul_f32_e32 v97, v97, v97
	v_mul_f32_e32 v86, v86, v86
	v_mul_f32_e32 v87, v87, v87
	v_mul_f32_e32 v88, v88, v88
	v_mul_f32_e32 v89, v89, v89
	v_cvt_pk_bf16_f32 v94, v94, v95
	v_cvt_pk_bf16_f32 v95, v96, v97
	v_cvt_pk_bf16_f32 v96, v86, v87
	v_cvt_pk_bf16_f32 v97, v88, v89
	s_nop 1
	v_permlane16_swap_b32_e32 v94, v96
	v_permlane16_swap_b32_e32 v95, v97
	global_store_dwordx4 v131, v[94:97], s[100:101]
	v_max_f32_e32 v90, 0, v90
	v_max_f32_e32 v91, 0, v91
	v_max_f32_e32 v92, 0, v92
	v_max_f32_e32 v93, 0, v93
	v_max_f32_e32 v82, 0, v82
	v_max_f32_e32 v83, 0, v83
	v_max_f32_e32 v84, 0, v84
	v_max_f32_e32 v85, 0, v85
	v_mul_f32_e32 v90, v90, v90
	v_mul_f32_e32 v91, v91, v91
	v_mul_f32_e32 v92, v92, v92
	v_mul_f32_e32 v93, v93, v93
	v_mul_f32_e32 v82, v82, v82
	v_mul_f32_e32 v83, v83, v83
	v_mul_f32_e32 v84, v84, v84
	v_mul_f32_e32 v85, v85, v85
	v_cvt_pk_bf16_f32 v90, v90, v91
	v_cvt_pk_bf16_f32 v91, v92, v93
	v_cvt_pk_bf16_f32 v92, v82, v83
	v_cvt_pk_bf16_f32 v93, v84, v85
	s_nop 1
	v_permlane16_swap_b32_e32 v90, v92
	v_permlane16_swap_b32_e32 v91, v93
	global_store_dwordx4 v131, v[90:93], s[100:101] offset:256
	s_add_u32 s100, s100, 0x20000
	s_addc_u32 s101, s101, 0
	v_max_f32_e32 v78, 0, v78
	v_max_f32_e32 v79, 0, v79
	v_max_f32_e32 v80, 0, v80
	v_max_f32_e32 v81, 0, v81
	v_max_f32_e32 v70, 0, v70
	v_max_f32_e32 v71, 0, v71
	v_max_f32_e32 v72, 0, v72
	v_max_f32_e32 v73, 0, v73
	v_mul_f32_e32 v78, v78, v78
	v_mul_f32_e32 v79, v79, v79
	v_mul_f32_e32 v80, v80, v80
	v_mul_f32_e32 v81, v81, v81
	v_mul_f32_e32 v70, v70, v70
	v_mul_f32_e32 v71, v71, v71
	v_mul_f32_e32 v72, v72, v72
	v_mul_f32_e32 v73, v73, v73
	v_cvt_pk_bf16_f32 v78, v78, v79
	v_cvt_pk_bf16_f32 v79, v80, v81
	v_cvt_pk_bf16_f32 v80, v70, v71
; __global__ void __launch_bounds__(512, 2) mega(Params P) {
;     ...
;         gemm256_unit<3>(UO, WUP, 1024, pm * 256, pn * 256, dyn_lds, [&](const acc4 (&acc)[2][2][4][2], int wr, int wc, int fr, int fq) {
; #pragma unroll
;           for (int ai = 0; ai < 2; ++ai)
; #pragma unroll
;             for (int m = 0; m < 4; ++m) {
;               const int row = pm * 256 + ai * 128 + wr * 64 + m * 16 + fr;
; #pragma unroll
;               for (int bj = 0; bj < 2; ++bj)
; #pragma unroll
;                 for (int n = 0; n < 2; ++n) {
;                   const int col = pn * 256 + bj * 128 + wc * 32 + n * 16 + fq * 4;
;                   const acc4 v = acc[ai][bj][m][n];
;                   const float v0 = fmaxf(v[0], 0.f), v1 = fmaxf(v[1], 0.f), v2 = fmaxf(v[2], 0.f), v3 = fmaxf(v[3], 0.f);
;                   u32x2 pk = {pack2(v0 * v0, v1 * v1), pack2(v2 * v2, v3 * v3)};
;                   *reinterpret_cast<u32x2*>(ABUF + (size_t)row * DFF + col) = pk;
;                 }
;             }
;         });
	v_cvt_pk_bf16_f32 v81, v72, v73
	s_nop 1
	v_permlane16_swap_b32_e32 v78, v80
	v_permlane16_swap_b32_e32 v79, v81
	global_store_dwordx4 v131, v[78:81], s[100:101]
	v_max_f32_e32 v74, 0, v74
	v_max_f32_e32 v75, 0, v75
	v_max_f32_e32 v76, 0, v76
	v_max_f32_e32 v77, 0, v77
	v_max_f32_e32 v66, 0, v66
	v_max_f32_e32 v67, 0, v67
	v_max_f32_e32 v68, 0, v68
	v_max_f32_e32 v69, 0, v69
	v_mul_f32_e32 v74, v74, v74
	v_mul_f32_e32 v75, v75, v75
	v_mul_f32_e32 v76, v76, v76
	v_mul_f32_e32 v77, v77, v77
	v_mul_f32_e32 v66, v66, v66
	v_mul_f32_e32 v67, v67, v67
	v_mul_f32_e32 v68, v68, v68
	v_mul_f32_e32 v69, v69, v69
	v_cvt_pk_bf16_f32 v74, v74, v75
	v_cvt_pk_bf16_f32 v75, v76, v77
	v_cvt_pk_bf16_f32 v76, v66, v67
	v_cvt_pk_bf16_f32 v77, v68, v69
	s_nop 1
	v_permlane16_swap_b32_e32 v74, v76
	v_permlane16_swap_b32_e32 v75, v77
	global_store_dwordx4 v131, v[74:77], s[100:101] offset:256
	s_add_u32 s100, s100, 0xa0000
	s_addc_u32 s101, s101, 0
	v_max_f32_e32 v62, 0, v62
	v_max_f32_e32 v63, 0, v63
	v_max_f32_e32 v64, 0, v64
	v_max_f32_e32 v65, 0, v65
	v_max_f32_e32 v58, 0, v58
	v_max_f32_e32 v59, 0, v59
	v_max_f32_e32 v60, 0, v60
	v_max_f32_e32 v61, 0, v61
	v_mul_f32_e32 v62, v62, v62
	v_mul_f32_e32 v63, v63, v63
	v_mul_f32_e32 v64, v64, v64
	v_mul_f32_e32 v65, v65, v65
	v_mul_f32_e32 v58, v58, v58
	v_mul_f32_e32 v59, v59, v59
	v_mul_f32_e32 v60, v60, v60
	v_mul_f32_e32 v61, v61, v61
	v_cvt_pk_bf16_f32 v62, v62, v63
	v_cvt_pk_bf16_f32 v63, v64, v65
	v_cvt_pk_bf16_f32 v64, v58, v59
	v_cvt_pk_bf16_f32 v65, v60, v61
	s_nop 1
	v_permlane16_swap_b32_e32 v62, v64
	v_permlane16_swap_b32_e32 v63, v65
	global_store_dwordx4 v131, v[62:65], s[100:101]
	v_max_f32_e32 v54, 0, v54
	v_max_f32_e32 v55, 0, v55
	v_max_f32_e32 v56, 0, v56
	v_max_f32_e32 v57, 0, v57
	v_max_f32_e32 v50, 0, v50
	v_max_f32_e32 v51, 0, v51
	v_max_f32_e32 v52, 0, v52
	v_max_f32_e32 v53, 0, v53
	v_mul_f32_e32 v54, v54, v54
	v_mul_f32_e32 v55, v55, v55
	v_mul_f32_e32 v56, v56, v56
	v_mul_f32_e32 v57, v57, v57
	v_mul_f32_e32 v50, v50, v50
	v_mul_f32_e32 v51, v51, v51
	v_mul_f32_e32 v52, v52, v52
	v_mul_f32_e32 v53, v53, v53
	v_cvt_pk_bf16_f32 v54, v54, v55
	v_cvt_pk_bf16_f32 v55, v56, v57
	v_cvt_pk_bf16_f32 v56, v50, v51
	v_cvt_pk_bf16_f32 v57, v52, v53
	s_nop 1
	v_permlane16_swap_b32_e32 v54, v56
	v_permlane16_swap_b32_e32 v55, v57
	global_store_dwordx4 v131, v[54:57], s[100:101] offset:256
	s_add_u32 s100, s100, 0x20000
	s_addc_u32 s101, s101, 0
	v_max_f32_e32 v46, 0, v46
	v_max_f32_e32 v47, 0, v47
	v_max_f32_e32 v48, 0, v48
	v_max_f32_e32 v49, 0, v49
	v_max_f32_e32 v42, 0, v42
	v_max_f32_e32 v43, 0, v43
	v_max_f32_e32 v44, 0, v44
	v_max_f32_e32 v45, 0, v45
	v_mul_f32_e32 v46, v46, v46
	v_mul_f32_e32 v47, v47, v47
	v_mul_f32_e32 v48, v48, v48
	v_mul_f32_e32 v49, v49, v49
	v_mul_f32_e32 v42, v42, v42
	v_mul_f32_e32 v43, v43, v43
	v_mul_f32_e32 v44, v44, v44
	v_mul_f32_e32 v45, v45, v45
	v_cvt_pk_bf16_f32 v46, v46, v47
	v_cvt_pk_bf16_f32 v47, v48, v49
	v_cvt_pk_bf16_f32 v48, v42, v43
	v_cvt_pk_bf16_f32 v49, v44, v45
	s_nop 1
	v_permlane16_swap_b32_e32 v46, v48
	v_permlane16_swap_b32_e32 v47, v49
	global_store_dwordx4 v131, v[46:49], s[100:101]
	v_max_f32_e32 v38, 0, v38
	v_max_f32_e32 v39, 0, v39
	v_max_f32_e32 v40, 0, v40
	v_max_f32_e32 v41, 0, v41
	v_max_f32_e32 v34, 0, v34
	v_max_f32_e32 v35, 0, v35
	v_max_f32_e32 v36, 0, v36
	v_max_f32_e32 v37, 0, v37
	v_mul_f32_e32 v38, v38, v38
	v_mul_f32_e32 v39, v39, v39
	v_mul_f32_e32 v40, v40, v40
	v_mul_f32_e32 v41, v41, v41
	v_mul_f32_e32 v34, v34, v34
	v_mul_f32_e32 v35, v35, v35
	v_mul_f32_e32 v36, v36, v36
	v_mul_f32_e32 v37, v37, v37
	v_cvt_pk_bf16_f32 v38, v38, v39
	v_cvt_pk_bf16_f32 v39, v40, v41
	v_cvt_pk_bf16_f32 v40, v34, v35
	v_cvt_pk_bf16_f32 v41, v36, v37
	s_nop 1
	v_permlane16_swap_b32_e32 v38, v40
	v_permlane16_swap_b32_e32 v39, v41
	global_store_dwordx4 v131, v[38:41], s[100:101] offset:256
	s_add_u32 s100, s100, 0x20000
	s_addc_u32 s101, s101, 0
	v_max_f32_e32 v30, 0, v30
	v_max_f32_e32 v31, 0, v31
	v_max_f32_e32 v32, 0, v32
	v_max_f32_e32 v33, 0, v33
	v_max_f32_e32 v26, 0, v26
	v_max_f32_e32 v27, 0, v27
	v_max_f32_e32 v28, 0, v28
	v_max_f32_e32 v29, 0, v29
	v_mul_f32_e32 v30, v30, v30
	v_mul_f32_e32 v31, v31, v31
	v_mul_f32_e32 v32, v32, v32
	v_mul_f32_e32 v33, v33, v33
	v_mul_f32_e32 v26, v26, v26
	v_mul_f32_e32 v27, v27, v27
	v_mul_f32_e32 v28, v28, v28
	v_mul_f32_e32 v29, v29, v29
	v_cvt_pk_bf16_f32 v30, v30, v31
	v_cvt_pk_bf16_f32 v31, v32, v33
	v_cvt_pk_bf16_f32 v32, v26, v27
	v_cvt_pk_bf16_f32 v33, v28, v29
	s_nop 1
	v_permlane16_swap_b32_e32 v30, v32
	v_permlane16_swap_b32_e32 v31, v33
	global_store_dwordx4 v131, v[30:33], s[100:101]
	v_max_f32_e32 v22, 0, v22
	v_max_f32_e32 v23, 0, v23
	v_max_f32_e32 v24, 0, v24
	v_max_f32_e32 v25, 0, v25
	v_max_f32_e32 v18, 0, v18
	v_max_f32_e32 v19, 0, v19
	v_max_f32_e32 v20, 0, v20
	v_max_f32_e32 v21, 0, v21
	v_mul_f32_e32 v22, v22, v22
	v_mul_f32_e32 v23, v23, v23
	v_mul_f32_e32 v24, v24, v24
	v_mul_f32_e32 v25, v25, v25
	v_mul_f32_e32 v18, v18, v18
	v_mul_f32_e32 v19, v19, v19
	v_mul_f32_e32 v20, v20, v20
	v_mul_f32_e32 v21, v21, v21
	v_cvt_pk_bf16_f32 v22, v22, v23
	v_cvt_pk_bf16_f32 v23, v24, v25
	v_cvt_pk_bf16_f32 v24, v18, v19
	v_cvt_pk_bf16_f32 v25, v20, v21
	s_nop 1
	v_permlane16_swap_b32_e32 v22, v24
	v_permlane16_swap_b32_e32 v23, v25
	global_store_dwordx4 v131, v[22:25], s[100:101] offset:256
	s_add_u32 s100, s100, 0x20000
	s_addc_u32 s101, s101, 0
	v_max_f32_e32 v14, 0, v14
	v_max_f32_e32 v15, 0, v15
	v_max_f32_e32 v16, 0, v16
	v_max_f32_e32 v17, 0, v17
	v_max_f32_e32 v10, 0, v10
	v_max_f32_e32 v11, 0, v11
	v_max_f32_e32 v12, 0, v12
	v_max_f32_e32 v13, 0, v13
	v_mul_f32_e32 v14, v14, v14
	v_mul_f32_e32 v15, v15, v15
	v_mul_f32_e32 v16, v16, v16
	v_mul_f32_e32 v17, v17, v17
	v_mul_f32_e32 v10, v10, v10
	v_mul_f32_e32 v11, v11, v11
	v_mul_f32_e32 v12, v12, v12
	v_mul_f32_e32 v13, v13, v13
	v_cvt_pk_bf16_f32 v14, v14, v15
	v_cvt_pk_bf16_f32 v15, v16, v17
	v_cvt_pk_bf16_f32 v16, v10, v11
	v_cvt_pk_bf16_f32 v17, v12, v13
	s_nop 1
	v_permlane16_swap_b32_e32 v14, v16
	v_permlane16_swap_b32_e32 v15, v17
	global_store_dwordx4 v131, v[14:17], s[100:101]
	v_max_f32_e32 v6, 0, v6
	v_max_f32_e32 v7, 0, v7
	v_max_f32_e32 v8, 0, v8
	v_max_f32_e32 v9, 0, v9
	v_max_f32_e32 v2, 0, v2
	v_max_f32_e32 v3, 0, v3
	v_max_f32_e32 v4, 0, v4
	v_max_f32_e32 v5, 0, v5
	v_mul_f32_e32 v6, v6, v6
	v_mul_f32_e32 v7, v7, v7
	v_mul_f32_e32 v8, v8, v8
	v_mul_f32_e32 v9, v9, v9
	v_mul_f32_e32 v2, v2, v2
	v_mul_f32_e32 v3, v3, v3
	v_mul_f32_e32 v4, v4, v4
	v_mul_f32_e32 v5, v5, v5
	v_cvt_pk_bf16_f32 v6, v6, v7
	v_cvt_pk_bf16_f32 v7, v8, v9
	v_cvt_pk_bf16_f32 v8, v2, v3
	v_cvt_pk_bf16_f32 v9, v4, v5
	s_nop 1
	v_permlane16_swap_b32_e32 v6, v8
	v_permlane16_swap_b32_e32 v7, v9
	global_store_dwordx4 v131, v[6:9], s[100:101] offset:256
	s_add_i32 s2, s2, 1
	s_mov_b64 s[26:27], 0
